# RMSNorm row loops (4 bf16 copies): the 16 row loads of the next iteration issued while the current rows are reduced/scaled/stored (software prefetch through spare registers)
# baseline (speedup 1.0000x reference)
.LBB0_98:
	v_readfirstlane_b32 s98, v82
	s_lshl_b32 s99, s46, 5
	s_cmp_lt_u32 s98, s99
	s_cbranch_scc1 .Lrms_first_0
	s_waitcnt vmcnt(0)
	v_ashrrev_i32_e32 v83, 31, v82
	v_lshlrev_b64 v[18:19], 12, v[82:83]
	v_lshl_add_u64 v[18:19], v[84:85], 0, v[18:19]
	v_mov_b64_e32 v[78:79], v[138:139]
	v_mov_b64_e32 v[80:81], v[140:141]
	v_mov_b64_e32 v[74:75], v[142:143]
	v_mov_b64_e32 v[76:77], v[144:145]
	v_mov_b64_e32 v[70:71], v[146:147]
	v_mov_b64_e32 v[72:73], v[148:149]
	v_mov_b64_e32 v[66:67], v[150:151]
	v_mov_b64_e32 v[68:69], v[152:153]
	v_or_b32_e32 v92, 1, v82
	v_min_i32_e32 v18, 0x7fff, v92
	v_ashrrev_i32_e32 v19, 31, v18
	v_lshlrev_b64 v[18:19], 12, v[18:19]
	v_lshl_add_u64 v[18:19], v[84:85], 0, v[18:19]
	v_mov_b64_e32 v[62:63], v[154:155]
	v_mov_b64_e32 v[64:65], v[156:157]
	v_mov_b64_e32 v[58:59], v[158:159]
	v_mov_b64_e32 v[60:61], v[160:161]
	v_mov_b64_e32 v[54:55], v[162:163]
	v_mov_b64_e32 v[56:57], v[164:165]
	v_mov_b64_e32 v[50:51], v[166:167]
	v_mov_b64_e32 v[52:53], v[168:169]
	v_or_b32_e32 v90, 2, v82
	v_min_i32_e32 v18, 0x7fff, v90
	v_ashrrev_i32_e32 v19, 31, v18
	v_lshlrev_b64 v[18:19], 12, v[18:19]
	v_lshl_add_u64 v[18:19], v[84:85], 0, v[18:19]
	v_or_b32_e32 v88, 3, v82
	v_mov_b64_e32 v[46:47], v[170:171]
	v_mov_b64_e32 v[48:49], v[172:173]
	v_mov_b64_e32 v[42:43], v[174:175]
	v_mov_b64_e32 v[44:45], v[176:177]
	v_mov_b64_e32 v[38:39], v[178:179]
	v_mov_b64_e32 v[40:41], v[180:181]
	s_waitcnt lgkmcnt(0)
	v_mov_b64_e32 v[34:35], v[182:183]
	v_mov_b64_e32 v[36:37], v[184:185]
	v_min_i32_e32 v18, 0x7fff, v88
	v_ashrrev_i32_e32 v19, 31, v18
	v_lshlrev_b64 v[18:19], 12, v[18:19]
	v_lshl_add_u64 v[18:19], v[84:85], 0, v[18:19]
	v_mov_b64_e32 v[30:31], v[186:187]
	v_mov_b64_e32 v[32:33], v[188:189]
	v_mov_b64_e32 v[26:27], v[190:191]
	v_mov_b64_e32 v[28:29], v[192:193]
	v_mov_b64_e32 v[22:23], v[194:195]
	v_mov_b64_e32 v[24:25], v[196:197]
	s_nop 0
	v_mov_b64_e32 v[18:19], v[208:209]
	v_mov_b64_e32 v[20:21], v[210:211]
	s_waitcnt lgkmcnt(0)
	s_branch .Lrms_common_0

.Lrms_common_0:
	s_lshl_b32 s99, s46, 5
	v_add_u32_e32 v212, s99, v82
	v_mov_b32_e32 v214, v212
	v_min_i32_e32 v214, 0x7fff, v214
	v_ashrrev_i32_e32 v215, 31, v214
	v_lshlrev_b64 v[214:215], 12, v[214:215]
	v_lshl_add_u64 v[214:215], v[84:85], 0, v[214:215]
	global_load_dwordx4 v[138:141], v[214:215], off
	global_load_dwordx4 v[142:145], v[214:215], off offset:1024
	global_load_dwordx4 v[146:149], v[214:215], off offset:2048
	global_load_dwordx4 v[150:153], v[214:215], off offset:3072
	v_or_b32_e32 v214, 1, v212
	v_min_i32_e32 v214, 0x7fff, v214
	v_ashrrev_i32_e32 v215, 31, v214
	v_lshlrev_b64 v[214:215], 12, v[214:215]
	v_lshl_add_u64 v[214:215], v[84:85], 0, v[214:215]
	global_load_dwordx4 v[154:157], v[214:215], off
	global_load_dwordx4 v[158:161], v[214:215], off offset:1024
	global_load_dwordx4 v[162:165], v[214:215], off offset:2048
	global_load_dwordx4 v[166:169], v[214:215], off offset:3072
	v_or_b32_e32 v214, 2, v212
	v_min_i32_e32 v214, 0x7fff, v214
	v_ashrrev_i32_e32 v215, 31, v214
	v_lshlrev_b64 v[214:215], 12, v[214:215]
	v_lshl_add_u64 v[214:215], v[84:85], 0, v[214:215]
	global_load_dwordx4 v[170:173], v[214:215], off
	global_load_dwordx4 v[174:177], v[214:215], off offset:1024
	global_load_dwordx4 v[178:181], v[214:215], off offset:2048
	global_load_dwordx4 v[182:185], v[214:215], off offset:3072
	v_or_b32_e32 v214, 3, v212
	v_min_i32_e32 v214, 0x7fff, v214
	v_ashrrev_i32_e32 v215, 31, v214
	v_lshlrev_b64 v[214:215], 12, v[214:215]
	v_lshl_add_u64 v[214:215], v[84:85], 0, v[214:215]
	global_load_dwordx4 v[186:189], v[214:215], off
	global_load_dwordx4 v[190:193], v[214:215], off offset:1024
	global_load_dwordx4 v[194:197], v[214:215], off offset:2048
	global_load_dwordx4 v[208:211], v[214:215], off offset:3072
	v_pk_mul_f32 v[100:101], v[80:81], v[80:81]
	v_pk_mul_f32 v[102:103], v[78:79], v[78:79]
	v_mul_f32_e32 v16, v66, v66
	v_pk_mov_b32 v[104:105], v[102:103], v[100:101] op_sel:[1,0]
	v_mov_b32_e32 v103, v101
	v_pk_add_f32 v[100:101], v[104:105], v[102:103]
	v_pk_mul_f32 v[102:103], v[76:77], v[76:77]
	v_pk_mul_f32 v[104:105], v[74:75], v[74:75]
	v_mul_f32_e32 v89, v67, v67
	v_pk_mov_b32 v[106:107], v[104:105], v[102:103] op_sel:[1,0]
	v_mov_b32_e32 v105, v103
	v_pk_add_f32 v[102:103], v[106:107], v[104:105]
	v_pk_add_f32 v[100:101], v[100:101], v[100:101] op_sel:[0,1] op_sel_hi:[1,0]
	v_pk_add_f32 v[102:103], v[102:103], v[102:103] op_sel:[0,1] op_sel_hi:[1,0]
	v_mov_b32_e32 v101, v16
	v_mov_b32_e32 v103, v89
	v_mul_f32_e32 v16, v71, v71
	v_pk_add_f32 v[100:101], v[100:101], v[102:103]
	v_pk_fma_f32 v[102:103], v[70:71], v[70:71], v[16:17] op_sel_hi:[1,1,0]
	v_mul_f32_e32 v16, v73, v73
	v_mul_f32_e32 v91, v68, v68
	v_mul_f32_e32 v93, v69, v69
	v_pk_fma_f32 v[104:105], v[72:73], v[72:73], v[16:17] op_sel_hi:[1,1,0]
	v_mov_b32_e32 v103, v91
	v_mov_b32_e32 v105, v93
	v_pk_add_f32 v[102:103], v[102:103], v[104:105]
	s_nop 0
	v_pk_add_f32 v[100:101], v[100:101], v[102:103]
	s_nop 0
	v_add_f32_e32 v16, v100, v101
	ds_bpermute_b32 v89, v94, v16
	v_lshlrev_b64 v[100:101], 11, v[82:83]
	v_lshl_add_u64 v[100:101], v[86:87], 0, v[100:101]
	s_waitcnt lgkmcnt(0)
	v_add_f32_e32 v16, v16, v89
	ds_bpermute_b32 v89, v95, v16
	s_waitcnt lgkmcnt(0)
	v_add_f32_e32 v16, v16, v89
	ds_bpermute_b32 v89, v96, v16
	s_waitcnt lgkmcnt(0)
	v_add_f32_e32 v16, v16, v89
	ds_bpermute_b32 v89, v97, v16
	s_waitcnt lgkmcnt(0)
	v_add_f32_e32 v16, v16, v89
	ds_bpermute_b32 v89, v98, v16
	s_waitcnt lgkmcnt(0)
	v_add_f32_e32 v16, v16, v89
	ds_bpermute_b32 v89, v99, v16
	s_waitcnt lgkmcnt(0)
	v_add_f32_e32 v16, v16, v89
	v_fmamk_f32 v16, v16, 0x3a800000, v231
	v_cmp_gt_f32_e32 vcc, s33, v16
	v_mul_f32_e32 v83, 0x4b800000, v16
	s_nop 0
	v_cndmask_b32_e32 v16, v16, v83, vcc
	v_rsq_f32_e32 v16, v16
	s_nop 0
	v_mul_f32_e32 v83, 0x45800000, v16
	v_cndmask_b32_e32 v16, v16, v83, vcc
	v_mul_f32_e32 v78, v78, v16
	v_mul_f32_e32 v79, v79, v16
	v_mul_f32_e32 v74, v74, v16
	v_mul_f32_e32 v75, v75, v16
	v_mul_f32_e32 v70, v70, v16
	v_mul_f32_e32 v71, v71, v16
	v_mul_f32_e32 v66, v66, v16
	v_mul_f32_e32 v67, v67, v16
	v_mul_f32_e32 v78, v0, v78
	v_mul_f32_e32 v79, v1, v79
	v_mul_f32_e32 v74, v4, v74
	v_mul_f32_e32 v75, v5, v75
	v_mul_f32_e32 v70, v8, v70
	v_mul_f32_e32 v71, v9, v71
	v_mul_f32_e32 v66, v12, v66
	v_mul_f32_e32 v67, v13, v67
	v_cvt_pk_bf16_f32 v78, v78, v79
	v_mul_f32_e32 v79, v80, v16
	v_mul_f32_e32 v80, v81, v16
	v_cvt_pk_bf16_f32 v74, v74, v75
	v_mul_f32_e32 v75, v76, v16
	v_mul_f32_e32 v76, v77, v16
	v_cvt_pk_bf16_f32 v70, v70, v71
	v_mul_f32_e32 v71, v72, v16
	v_mul_f32_e32 v72, v73, v16
	v_cvt_pk_bf16_f32 v66, v66, v67
	v_mul_f32_e32 v67, v68, v16
	v_mul_f32_e32 v16, v69, v16
	v_mul_f32_e32 v67, v14, v67
	v_mul_f32_e32 v16, v15, v16
	v_cvt_pk_bf16_f32 v67, v67, v16
	global_store_dwordx2 v[100:101], v[66:67], off offset:1536
	v_mul_f32_e32 v16, v63, v63
	v_mul_f32_e32 v66, v65, v65
	v_fmac_f32_e32 v16, v62, v62
	v_fmac_f32_e32 v66, v64, v64
	v_add_f32_e32 v16, v16, v66
	v_mul_f32_e32 v66, v59, v59
	v_mul_f32_e32 v67, v61, v61
	v_fmac_f32_e32 v66, v58, v58
	v_fmac_f32_e32 v67, v60, v60
	v_add_f32_e32 v66, v66, v67
	v_add_f32_e32 v16, v16, v66
	v_mul_f32_e32 v66, v55, v55
	v_mul_f32_e32 v67, v57, v57
	v_fmac_f32_e32 v66, v54, v54
	v_fmac_f32_e32 v67, v56, v56
	v_add_f32_e32 v66, v66, v67
	v_add_f32_e32 v16, v16, v66
	v_mul_f32_e32 v66, v51, v51
	v_mul_f32_e32 v67, v53, v53
	v_fmac_f32_e32 v66, v50, v50
	v_fmac_f32_e32 v67, v52, v52
	v_add_f32_e32 v66, v66, v67
	v_add_f32_e32 v16, v16, v66
	ds_bpermute_b32 v66, v94, v16
	v_mul_f32_e32 v79, v2, v79
	v_mul_f32_e32 v75, v6, v75
	v_mul_f32_e32 v71, v10, v71
	v_cmp_gt_i32_e32 vcc, s47, v92
	s_waitcnt lgkmcnt(0)
	v_add_f32_e32 v16, v16, v66
	ds_bpermute_b32 v66, v95, v16
	v_mul_f32_e32 v80, v3, v80
	v_cvt_pk_bf16_f32 v79, v79, v80
	global_store_dwordx2 v[100:101], v[78:79], off
	v_mul_f32_e32 v76, v7, v76
	s_waitcnt lgkmcnt(0)
	v_add_f32_e32 v16, v16, v66
	ds_bpermute_b32 v66, v96, v16
	v_cvt_pk_bf16_f32 v75, v75, v76
	global_store_dwordx2 v[100:101], v[74:75], off offset:512
	v_mul_f32_e32 v72, v11, v72
	v_cvt_pk_bf16_f32 v71, v71, v72
	s_waitcnt lgkmcnt(0)
	v_add_f32_e32 v16, v16, v66
	ds_bpermute_b32 v66, v97, v16
	global_store_dwordx2 v[100:101], v[70:71], off offset:1024
	s_waitcnt lgkmcnt(0)
	v_add_f32_e32 v16, v16, v66
	ds_bpermute_b32 v66, v98, v16
	s_waitcnt lgkmcnt(0)
	v_add_f32_e32 v16, v16, v66
	ds_bpermute_b32 v66, v99, v16
	s_and_saveexec_b64 s[22:23], vcc
	s_cbranch_execz .LBB0_100
	s_waitcnt lgkmcnt(0)
	v_add_f32_e32 v16, v16, v66
	v_fmamk_f32 v16, v16, 0x3a800000, v231
	v_mul_f32_e32 v66, 0x4b800000, v16
	v_cmp_gt_f32_e32 vcc, s33, v16
	v_ashrrev_i32_e32 v93, 31, v92
	s_nop 0
	v_cndmask_b32_e32 v16, v16, v66, vcc
	v_rsq_f32_e32 v16, v16
	v_lshlrev_b64 v[66:67], 11, v[92:93]
	v_lshl_add_u64 v[66:67], v[86:87], 0, v[66:67]
	v_mul_f32_e32 v68, 0x45800000, v16
	v_cndmask_b32_e32 v16, v16, v68, vcc
	v_mul_f32_e32 v62, v62, v16
	v_mul_f32_e32 v63, v63, v16
	v_mul_f32_e32 v58, v58, v16
	v_mul_f32_e32 v59, v59, v16
	v_mul_f32_e32 v54, v54, v16
	v_mul_f32_e32 v55, v55, v16
	v_mul_f32_e32 v50, v50, v16
	v_mul_f32_e32 v51, v51, v16
	v_mul_f32_e32 v62, v0, v62
	v_mul_f32_e32 v63, v1, v63
	v_mul_f32_e32 v58, v4, v58
	v_mul_f32_e32 v59, v5, v59
	v_mul_f32_e32 v54, v8, v54
	v_mul_f32_e32 v55, v9, v55
	v_mul_f32_e32 v50, v12, v50
	v_mul_f32_e32 v51, v13, v51
	v_cvt_pk_bf16_f32 v62, v62, v63
	v_mul_f32_e32 v63, v64, v16
	v_cvt_pk_bf16_f32 v58, v58, v59
	v_mul_f32_e32 v59, v60, v16
	v_cvt_pk_bf16_f32 v54, v54, v55
	v_mul_f32_e32 v55, v56, v16
	v_cvt_pk_bf16_f32 v50, v50, v51
	v_mul_f32_e32 v51, v52, v16
	v_mul_f32_e32 v63, v2, v63
	v_mul_f32_e32 v64, v65, v16
	v_mul_f32_e32 v59, v6, v59
	v_mul_f32_e32 v60, v61, v16
	v_mul_f32_e32 v55, v10, v55
	v_mul_f32_e32 v56, v57, v16
	v_mul_f32_e32 v51, v14, v51
	v_mul_f32_e32 v16, v53, v16
	v_mul_f32_e32 v64, v3, v64
	v_cvt_pk_bf16_f32 v63, v63, v64
	global_store_dwordx2 v[66:67], v[62:63], off
	v_mul_f32_e32 v60, v7, v60
	v_cvt_pk_bf16_f32 v59, v59, v60
	global_store_dwordx2 v[66:67], v[58:59], off offset:512
	v_mul_f32_e32 v56, v11, v56
	v_cvt_pk_bf16_f32 v55, v55, v56
	global_store_dwordx2 v[66:67], v[54:55], off offset:1024
	v_mul_f32_e32 v16, v15, v16
	v_cvt_pk_bf16_f32 v51, v51, v16
	global_store_dwordx2 v[66:67], v[50:51], off offset:1536

.LBB0_183:
	v_readfirstlane_b32 s98, v82
	s_lshl_b32 s99, s46, 5
	s_cmp_lt_u32 s98, s99
	s_cbranch_scc1 .Lrms_first_1
	s_waitcnt vmcnt(0)
	v_ashrrev_i32_e32 v83, 31, v82
	v_lshlrev_b64 v[18:19], 12, v[82:83]
	v_lshl_add_u64 v[18:19], v[84:85], 0, v[18:19]
	v_mov_b64_e32 v[78:79], v[138:139]
	v_mov_b64_e32 v[80:81], v[140:141]
	v_mov_b64_e32 v[74:75], v[142:143]
	v_mov_b64_e32 v[76:77], v[144:145]
	v_mov_b64_e32 v[70:71], v[146:147]
	v_mov_b64_e32 v[72:73], v[148:149]
	v_mov_b64_e32 v[66:67], v[150:151]
	v_mov_b64_e32 v[68:69], v[152:153]
	v_or_b32_e32 v92, 1, v82
	v_min_i32_e32 v18, 0x3fff, v92
	v_ashrrev_i32_e32 v19, 31, v18
	v_lshlrev_b64 v[18:19], 12, v[18:19]
	v_lshl_add_u64 v[18:19], v[84:85], 0, v[18:19]
	v_mov_b64_e32 v[62:63], v[154:155]
	v_mov_b64_e32 v[64:65], v[156:157]
	v_mov_b64_e32 v[58:59], v[158:159]
	v_mov_b64_e32 v[60:61], v[160:161]
	v_mov_b64_e32 v[54:55], v[162:163]
	v_mov_b64_e32 v[56:57], v[164:165]
	v_mov_b64_e32 v[50:51], v[166:167]
	v_mov_b64_e32 v[52:53], v[168:169]
	v_or_b32_e32 v90, 2, v82
	v_min_i32_e32 v18, 0x3fff, v90
	v_ashrrev_i32_e32 v19, 31, v18
	v_lshlrev_b64 v[18:19], 12, v[18:19]
	v_lshl_add_u64 v[18:19], v[84:85], 0, v[18:19]
	v_or_b32_e32 v88, 3, v82
	v_mov_b64_e32 v[46:47], v[170:171]
	v_mov_b64_e32 v[48:49], v[172:173]
	v_mov_b64_e32 v[42:43], v[174:175]
	v_mov_b64_e32 v[44:45], v[176:177]
	v_mov_b64_e32 v[38:39], v[178:179]
	v_mov_b64_e32 v[40:41], v[180:181]
	s_waitcnt lgkmcnt(0)
	v_mov_b64_e32 v[34:35], v[182:183]
	v_mov_b64_e32 v[36:37], v[184:185]
	v_min_i32_e32 v18, 0x3fff, v88
	v_ashrrev_i32_e32 v19, 31, v18
	v_lshlrev_b64 v[18:19], 12, v[18:19]
	v_lshl_add_u64 v[18:19], v[84:85], 0, v[18:19]
	v_mov_b64_e32 v[30:31], v[186:187]
	v_mov_b64_e32 v[32:33], v[188:189]
	v_mov_b64_e32 v[26:27], v[190:191]
	v_mov_b64_e32 v[28:29], v[192:193]
	v_mov_b64_e32 v[22:23], v[194:195]
	v_mov_b64_e32 v[24:25], v[196:197]
	s_nop 0
	v_mov_b64_e32 v[18:19], v[208:209]
	v_mov_b64_e32 v[20:21], v[210:211]
	s_waitcnt lgkmcnt(0)
	s_branch .Lrms_common_1

.Lrms_common_1:
	s_lshl_b32 s99, s46, 5
	v_add_u32_e32 v212, s99, v82
	v_mov_b32_e32 v214, v212
	v_min_i32_e32 v214, 0x3fff, v214
	v_ashrrev_i32_e32 v215, 31, v214
	v_lshlrev_b64 v[214:215], 12, v[214:215]
	v_lshl_add_u64 v[214:215], v[84:85], 0, v[214:215]
	global_load_dwordx4 v[138:141], v[214:215], off
	global_load_dwordx4 v[142:145], v[214:215], off offset:1024
	global_load_dwordx4 v[146:149], v[214:215], off offset:2048
	global_load_dwordx4 v[150:153], v[214:215], off offset:3072
	v_or_b32_e32 v214, 1, v212
	v_min_i32_e32 v214, 0x3fff, v214
	v_ashrrev_i32_e32 v215, 31, v214
	v_lshlrev_b64 v[214:215], 12, v[214:215]
	v_lshl_add_u64 v[214:215], v[84:85], 0, v[214:215]
	global_load_dwordx4 v[154:157], v[214:215], off
	global_load_dwordx4 v[158:161], v[214:215], off offset:1024
	global_load_dwordx4 v[162:165], v[214:215], off offset:2048
	global_load_dwordx4 v[166:169], v[214:215], off offset:3072
	v_or_b32_e32 v214, 2, v212
	v_min_i32_e32 v214, 0x3fff, v214
	v_ashrrev_i32_e32 v215, 31, v214
	v_lshlrev_b64 v[214:215], 12, v[214:215]
	v_lshl_add_u64 v[214:215], v[84:85], 0, v[214:215]
	global_load_dwordx4 v[170:173], v[214:215], off
	global_load_dwordx4 v[174:177], v[214:215], off offset:1024
	global_load_dwordx4 v[178:181], v[214:215], off offset:2048
	global_load_dwordx4 v[182:185], v[214:215], off offset:3072
	v_or_b32_e32 v214, 3, v212
	v_min_i32_e32 v214, 0x3fff, v214
	v_ashrrev_i32_e32 v215, 31, v214
	v_lshlrev_b64 v[214:215], 12, v[214:215]
	v_lshl_add_u64 v[214:215], v[84:85], 0, v[214:215]
	global_load_dwordx4 v[186:189], v[214:215], off
	global_load_dwordx4 v[190:193], v[214:215], off offset:1024
	global_load_dwordx4 v[194:197], v[214:215], off offset:2048
	global_load_dwordx4 v[208:211], v[214:215], off offset:3072
	v_pk_mul_f32 v[100:101], v[80:81], v[80:81]
	v_pk_mul_f32 v[102:103], v[78:79], v[78:79]
	v_mul_f32_e32 v16, v66, v66
	v_pk_mov_b32 v[104:105], v[102:103], v[100:101] op_sel:[1,0]
	v_mov_b32_e32 v103, v101
	v_pk_add_f32 v[100:101], v[104:105], v[102:103]
	v_pk_mul_f32 v[102:103], v[76:77], v[76:77]
	v_pk_mul_f32 v[104:105], v[74:75], v[74:75]
	v_mul_f32_e32 v89, v67, v67
	v_pk_mov_b32 v[106:107], v[104:105], v[102:103] op_sel:[1,0]
	v_mov_b32_e32 v105, v103
	v_pk_add_f32 v[102:103], v[106:107], v[104:105]
	v_pk_add_f32 v[100:101], v[100:101], v[100:101] op_sel:[0,1] op_sel_hi:[1,0]
	v_pk_add_f32 v[102:103], v[102:103], v[102:103] op_sel:[0,1] op_sel_hi:[1,0]
	v_mov_b32_e32 v101, v16
	v_mov_b32_e32 v103, v89
	v_mul_f32_e32 v16, v71, v71
	v_pk_add_f32 v[100:101], v[100:101], v[102:103]
	v_pk_fma_f32 v[102:103], v[70:71], v[70:71], v[16:17] op_sel_hi:[1,1,0]
	v_mul_f32_e32 v16, v73, v73
	v_mul_f32_e32 v91, v68, v68
	v_mul_f32_e32 v93, v69, v69
	v_pk_fma_f32 v[104:105], v[72:73], v[72:73], v[16:17] op_sel_hi:[1,1,0]
	v_mov_b32_e32 v103, v91
	v_mov_b32_e32 v105, v93
	v_pk_add_f32 v[102:103], v[102:103], v[104:105]
	s_nop 0
	v_pk_add_f32 v[100:101], v[100:101], v[102:103]
	s_nop 0
	v_add_f32_e32 v16, v100, v101
	ds_bpermute_b32 v89, v94, v16
	v_lshlrev_b64 v[100:101], 11, v[82:83]
	v_lshl_add_u64 v[100:101], v[86:87], 0, v[100:101]
	s_waitcnt lgkmcnt(0)
	v_add_f32_e32 v16, v16, v89
	ds_bpermute_b32 v89, v95, v16
	s_waitcnt lgkmcnt(0)
	v_add_f32_e32 v16, v16, v89
	ds_bpermute_b32 v89, v96, v16
	s_waitcnt lgkmcnt(0)
	v_add_f32_e32 v16, v16, v89
	ds_bpermute_b32 v89, v97, v16
	s_waitcnt lgkmcnt(0)
	v_add_f32_e32 v16, v16, v89
	ds_bpermute_b32 v89, v98, v16
	s_waitcnt lgkmcnt(0)
	v_add_f32_e32 v16, v16, v89
	ds_bpermute_b32 v89, v99, v16
	s_waitcnt lgkmcnt(0)
	v_add_f32_e32 v16, v16, v89
	v_fmamk_f32 v16, v16, 0x3a800000, v231
	v_cmp_gt_f32_e32 vcc, s33, v16
	v_mul_f32_e32 v83, 0x4b800000, v16
	s_nop 0
	v_cndmask_b32_e32 v16, v16, v83, vcc
	v_rsq_f32_e32 v16, v16
	s_nop 0
	v_mul_f32_e32 v83, 0x45800000, v16
	v_cndmask_b32_e32 v16, v16, v83, vcc
	v_mul_f32_e32 v78, v78, v16
	v_mul_f32_e32 v79, v79, v16
	v_mul_f32_e32 v74, v74, v16
	v_mul_f32_e32 v75, v75, v16
	v_mul_f32_e32 v70, v70, v16
	v_mul_f32_e32 v71, v71, v16
	v_mul_f32_e32 v66, v66, v16
	v_mul_f32_e32 v67, v67, v16
	v_mul_f32_e32 v78, v0, v78
	v_mul_f32_e32 v79, v1, v79
	v_mul_f32_e32 v74, v4, v74
	v_mul_f32_e32 v75, v5, v75
	v_mul_f32_e32 v70, v8, v70
	v_mul_f32_e32 v71, v9, v71
	v_mul_f32_e32 v66, v12, v66
	v_mul_f32_e32 v67, v13, v67
	v_cvt_pk_bf16_f32 v78, v78, v79
	v_mul_f32_e32 v79, v80, v16
	v_mul_f32_e32 v80, v81, v16
	v_cvt_pk_bf16_f32 v74, v74, v75
	v_mul_f32_e32 v75, v76, v16
	v_mul_f32_e32 v76, v77, v16
	v_cvt_pk_bf16_f32 v70, v70, v71
	v_mul_f32_e32 v71, v72, v16
	v_mul_f32_e32 v72, v73, v16
	v_cvt_pk_bf16_f32 v66, v66, v67
	v_mul_f32_e32 v67, v68, v16
	v_mul_f32_e32 v16, v69, v16
	v_mul_f32_e32 v67, v14, v67
	v_mul_f32_e32 v16, v15, v16
	v_cvt_pk_bf16_f32 v67, v67, v16
	global_store_dwordx2 v[100:101], v[66:67], off offset:1536
	v_mul_f32_e32 v16, v63, v63
	v_mul_f32_e32 v66, v65, v65
	v_fmac_f32_e32 v16, v62, v62
	v_fmac_f32_e32 v66, v64, v64
	v_add_f32_e32 v16, v16, v66
	v_mul_f32_e32 v66, v59, v59
	v_mul_f32_e32 v67, v61, v61
	v_fmac_f32_e32 v66, v58, v58
	v_fmac_f32_e32 v67, v60, v60
	v_add_f32_e32 v66, v66, v67
	v_add_f32_e32 v16, v16, v66
	v_mul_f32_e32 v66, v55, v55
	v_mul_f32_e32 v67, v57, v57
	v_fmac_f32_e32 v66, v54, v54
	v_fmac_f32_e32 v67, v56, v56
	v_add_f32_e32 v66, v66, v67
	v_add_f32_e32 v16, v16, v66
	v_mul_f32_e32 v66, v51, v51
	v_mul_f32_e32 v67, v53, v53
	v_fmac_f32_e32 v66, v50, v50
	v_fmac_f32_e32 v67, v52, v52
	v_add_f32_e32 v66, v66, v67
	v_add_f32_e32 v16, v16, v66
	ds_bpermute_b32 v66, v94, v16
	v_mul_f32_e32 v79, v2, v79
	v_mul_f32_e32 v75, v6, v75
	v_mul_f32_e32 v71, v10, v71
	v_cmp_gt_i32_e32 vcc, s62, v92
	s_waitcnt lgkmcnt(0)
	v_add_f32_e32 v16, v16, v66
	ds_bpermute_b32 v66, v95, v16
	v_mul_f32_e32 v80, v3, v80
	v_cvt_pk_bf16_f32 v79, v79, v80
	global_store_dwordx2 v[100:101], v[78:79], off
	v_mul_f32_e32 v76, v7, v76
	s_waitcnt lgkmcnt(0)
	v_add_f32_e32 v16, v16, v66
	ds_bpermute_b32 v66, v96, v16
	v_cvt_pk_bf16_f32 v75, v75, v76
	global_store_dwordx2 v[100:101], v[74:75], off offset:512
	v_mul_f32_e32 v72, v11, v72
	v_cvt_pk_bf16_f32 v71, v71, v72
	s_waitcnt lgkmcnt(0)
	v_add_f32_e32 v16, v16, v66
	ds_bpermute_b32 v66, v97, v16
	global_store_dwordx2 v[100:101], v[70:71], off offset:1024
	s_waitcnt lgkmcnt(0)
	v_add_f32_e32 v16, v16, v66
	ds_bpermute_b32 v66, v98, v16
	s_waitcnt lgkmcnt(0)
	v_add_f32_e32 v16, v16, v66
	ds_bpermute_b32 v66, v99, v16
	s_and_saveexec_b64 s[14:15], vcc
	s_cbranch_execz .LBB0_185
	s_waitcnt lgkmcnt(0)
	v_add_f32_e32 v16, v16, v66
	v_fmamk_f32 v16, v16, 0x3a800000, v231
	v_mul_f32_e32 v66, 0x4b800000, v16
	v_cmp_gt_f32_e32 vcc, s33, v16
	v_ashrrev_i32_e32 v93, 31, v92
	s_nop 0
	v_cndmask_b32_e32 v16, v16, v66, vcc
	v_rsq_f32_e32 v16, v16
	v_lshlrev_b64 v[66:67], 11, v[92:93]
	v_lshl_add_u64 v[66:67], v[86:87], 0, v[66:67]
	v_mul_f32_e32 v68, 0x45800000, v16
	v_cndmask_b32_e32 v16, v16, v68, vcc
	v_mul_f32_e32 v62, v62, v16
	v_mul_f32_e32 v63, v63, v16
	v_mul_f32_e32 v58, v58, v16
	v_mul_f32_e32 v59, v59, v16
	v_mul_f32_e32 v54, v54, v16
	v_mul_f32_e32 v55, v55, v16
	v_mul_f32_e32 v50, v50, v16
	v_mul_f32_e32 v51, v51, v16
	v_mul_f32_e32 v62, v0, v62
	v_mul_f32_e32 v63, v1, v63
	v_mul_f32_e32 v58, v4, v58
	v_mul_f32_e32 v59, v5, v59
	v_mul_f32_e32 v54, v8, v54
	v_mul_f32_e32 v55, v9, v55
	v_mul_f32_e32 v50, v12, v50
	v_mul_f32_e32 v51, v13, v51
	v_cvt_pk_bf16_f32 v62, v62, v63
	v_mul_f32_e32 v63, v64, v16
	v_cvt_pk_bf16_f32 v58, v58, v59
	v_mul_f32_e32 v59, v60, v16
	v_cvt_pk_bf16_f32 v54, v54, v55
	v_mul_f32_e32 v55, v56, v16
	v_cvt_pk_bf16_f32 v50, v50, v51
	v_mul_f32_e32 v51, v52, v16
	v_mul_f32_e32 v63, v2, v63
	v_mul_f32_e32 v64, v65, v16
	v_mul_f32_e32 v59, v6, v59
	v_mul_f32_e32 v60, v61, v16
	v_mul_f32_e32 v55, v10, v55
	v_mul_f32_e32 v56, v57, v16
	v_mul_f32_e32 v51, v14, v51
	v_mul_f32_e32 v16, v53, v16
	v_mul_f32_e32 v64, v3, v64
	v_cvt_pk_bf16_f32 v63, v63, v64
	global_store_dwordx2 v[66:67], v[62:63], off
	v_mul_f32_e32 v60, v7, v60
	v_cvt_pk_bf16_f32 v59, v59, v60
	global_store_dwordx2 v[66:67], v[58:59], off offset:512
	v_mul_f32_e32 v56, v11, v56
	v_cvt_pk_bf16_f32 v55, v55, v56
	global_store_dwordx2 v[66:67], v[54:55], off offset:1024
	v_mul_f32_e32 v16, v15, v16
	v_cvt_pk_bf16_f32 v51, v51, v16
	global_store_dwordx2 v[66:67], v[50:51], off offset:1536

.LBB0_1150:
	v_readfirstlane_b32 s98, v74
	s_lshl_b32 s99, s46, 5
	s_cmp_lt_u32 s98, s99
	s_cbranch_scc1 .Lrms_first_3
	s_waitcnt vmcnt(0)
	v_ashrrev_i32_e32 v75, 31, v74
	v_lshlrev_b64 v[18:19], 12, v[74:75]
	v_lshl_add_u64 v[18:19], v[76:77], 0, v[18:19]
	v_mov_b64_e32 v[92:93], v[138:139]
	v_mov_b64_e32 v[94:95], v[140:141]
	v_mov_b64_e32 v[96:97], v[142:143]
	v_mov_b64_e32 v[98:99], v[144:145]
	v_mov_b64_e32 v[66:67], v[150:151]
	v_mov_b64_e32 v[68:69], v[152:153]
	v_mov_b64_e32 v[70:71], v[146:147]
	v_mov_b64_e32 v[72:73], v[148:149]
	v_or_b32_e32 v84, 1, v74
	v_min_i32_e32 v18, 0x7fff, v84
	v_ashrrev_i32_e32 v19, 31, v18
	v_lshlrev_b64 v[18:19], 12, v[18:19]
	v_lshl_add_u64 v[18:19], v[76:77], 0, v[18:19]
	v_mov_b64_e32 v[62:63], v[154:155]
	v_mov_b64_e32 v[64:65], v[156:157]
	v_mov_b64_e32 v[58:59], v[158:159]
	v_mov_b64_e32 v[60:61], v[160:161]
	v_mov_b64_e32 v[54:55], v[162:163]
	v_mov_b64_e32 v[56:57], v[164:165]
	v_mov_b64_e32 v[50:51], v[166:167]
	v_mov_b64_e32 v[52:53], v[168:169]
	v_or_b32_e32 v82, 2, v74
	v_or_b32_e32 v80, 3, v74
	v_min_i32_e32 v18, 0x7fff, v82
	v_min_i32_e32 v20, 0x7fff, v80
	v_ashrrev_i32_e32 v19, 31, v18
	v_ashrrev_i32_e32 v21, 31, v20
	v_lshlrev_b64 v[18:19], 12, v[18:19]
	v_lshlrev_b64 v[20:21], 12, v[20:21]
	v_lshl_add_u64 v[18:19], v[76:77], 0, v[18:19]
	v_lshl_add_u64 v[20:21], v[76:77], 0, v[20:21]
	v_mov_b64_e32 v[46:47], v[170:171]
	v_mov_b64_e32 v[48:49], v[172:173]
	v_mov_b64_e32 v[42:43], v[174:175]
	v_mov_b64_e32 v[44:45], v[176:177]
	v_mov_b64_e32 v[38:39], v[178:179]
	v_mov_b64_e32 v[40:41], v[180:181]
	s_waitcnt lgkmcnt(0)
	v_mov_b64_e32 v[34:35], v[182:183]
	v_mov_b64_e32 v[36:37], v[184:185]
	v_mov_b64_e32 v[30:31], v[186:187]
	v_mov_b64_e32 v[32:33], v[188:189]
	v_mov_b64_e32 v[26:27], v[190:191]
	v_mov_b64_e32 v[28:29], v[192:193]
	v_mov_b64_e32 v[22:23], v[194:195]
	v_mov_b64_e32 v[24:25], v[196:197]
	s_nop 0
	v_mov_b64_e32 v[18:19], v[208:209]
	v_mov_b64_e32 v[20:21], v[210:211]
	s_waitcnt lgkmcnt(0)
	s_branch .Lrms_common_3

.Lrms_common_3:
	s_lshl_b32 s99, s46, 5
	v_add_u32_e32 v212, s99, v74
	v_mov_b32_e32 v214, v212
	v_min_i32_e32 v214, 0x7fff, v214
	v_ashrrev_i32_e32 v215, 31, v214
	v_lshlrev_b64 v[214:215], 12, v[214:215]
	v_lshl_add_u64 v[214:215], v[76:77], 0, v[214:215]
	global_load_dwordx4 v[138:141], v[214:215], off
	global_load_dwordx4 v[142:145], v[214:215], off offset:1024
	global_load_dwordx4 v[146:149], v[214:215], off offset:2048
	global_load_dwordx4 v[150:153], v[214:215], off offset:3072
	v_or_b32_e32 v214, 1, v212
	v_min_i32_e32 v214, 0x7fff, v214
	v_ashrrev_i32_e32 v215, 31, v214
	v_lshlrev_b64 v[214:215], 12, v[214:215]
	v_lshl_add_u64 v[214:215], v[76:77], 0, v[214:215]
	global_load_dwordx4 v[154:157], v[214:215], off
	global_load_dwordx4 v[158:161], v[214:215], off offset:1024
	global_load_dwordx4 v[162:165], v[214:215], off offset:2048
	global_load_dwordx4 v[166:169], v[214:215], off offset:3072
	v_or_b32_e32 v214, 2, v212
	v_min_i32_e32 v214, 0x7fff, v214
	v_ashrrev_i32_e32 v215, 31, v214
	v_lshlrev_b64 v[214:215], 12, v[214:215]
	v_lshl_add_u64 v[214:215], v[76:77], 0, v[214:215]
	global_load_dwordx4 v[170:173], v[214:215], off
	global_load_dwordx4 v[174:177], v[214:215], off offset:1024
	global_load_dwordx4 v[178:181], v[214:215], off offset:2048
	global_load_dwordx4 v[182:185], v[214:215], off offset:3072
	v_or_b32_e32 v214, 3, v212
	v_min_i32_e32 v214, 0x7fff, v214
	v_ashrrev_i32_e32 v215, 31, v214
	v_lshlrev_b64 v[214:215], 12, v[214:215]
	v_lshl_add_u64 v[214:215], v[76:77], 0, v[214:215]
	global_load_dwordx4 v[186:189], v[214:215], off
	global_load_dwordx4 v[190:193], v[214:215], off offset:1024
	global_load_dwordx4 v[194:197], v[214:215], off offset:2048
	global_load_dwordx4 v[208:211], v[214:215], off offset:3072
	v_pk_mul_f32 v[100:101], v[94:95], v[94:95]
	v_pk_mul_f32 v[102:103], v[92:93], v[92:93]
	v_pk_mul_f32 v[104:105], v[98:99], v[98:99]
	v_pk_mul_f32 v[106:107], v[96:97], v[96:97]
	v_pk_mov_b32 v[110:111], v[102:103], v[100:101] op_sel:[1,0]
	v_mov_b32_e32 v103, v101
	v_pk_mov_b32 v[100:101], v[106:107], v[104:105] op_sel:[1,0]
	v_mov_b32_e32 v107, v105
	v_mul_f32_e32 v16, v71, v71
	v_mul_f32_e32 v108, v73, v73
	v_pk_add_f32 v[102:103], v[110:111], v[102:103]
	v_pk_add_f32 v[100:101], v[100:101], v[106:107]
	v_mul_f32_e32 v81, v66, v66
	v_mul_f32_e32 v83, v67, v67
	v_mul_f32_e32 v85, v68, v68
	v_mul_f32_e32 v112, v69, v69
	v_pk_fma_f32 v[104:105], v[70:71], v[70:71], v[16:17] op_sel_hi:[1,1,0]
	v_pk_fma_f32 v[108:109], v[72:73], v[72:73], v[108:109] op_sel_hi:[1,1,0]
	v_pk_add_f32 v[102:103], v[102:103], v[102:103] op_sel:[0,1] op_sel_hi:[1,0]
	v_pk_add_f32 v[100:101], v[100:101], v[100:101] op_sel:[0,1] op_sel_hi:[1,0]
	v_mov_b32_e32 v105, v85
	v_mov_b32_e32 v109, v112
	v_mov_b32_e32 v103, v81
	v_mov_b32_e32 v101, v83
	v_pk_add_f32 v[104:105], v[104:105], v[108:109]
	v_pk_add_f32 v[100:101], v[102:103], v[100:101]
	v_mul_f32_e32 v16, v63, v63
	v_pk_add_f32 v[100:101], v[100:101], v[104:105]
	v_mul_f32_e32 v85, v65, v65
	v_add_f32_e32 v81, v100, v101
	ds_bpermute_b32 v83, v86, v81
	v_mul_f32_e32 v106, v59, v59
	v_mul_f32_e32 v107, v61, v61
	v_mul_f32_e32 v100, v55, v55
	v_mul_f32_e32 v101, v57, v57
	s_waitcnt lgkmcnt(0)
	v_add_f32_e32 v81, v81, v83
	ds_bpermute_b32 v83, v87, v81
	v_fmac_f32_e32 v16, v62, v62
	v_fmac_f32_e32 v85, v64, v64
	v_fmac_f32_e32 v106, v58, v58
	v_fmac_f32_e32 v107, v60, v60
	s_waitcnt lgkmcnt(0)
	v_add_f32_e32 v81, v81, v83
	ds_bpermute_b32 v83, v88, v81
	v_mul_f32_e32 v102, v51, v51
	v_mul_f32_e32 v103, v53, v53
	v_fmac_f32_e32 v100, v54, v54
	v_fmac_f32_e32 v101, v56, v56
	s_waitcnt lgkmcnt(0)
	v_add_f32_e32 v81, v81, v83
	ds_bpermute_b32 v83, v89, v81
	v_add_f32_e32 v16, v16, v85
	v_add_f32_e32 v85, v106, v107
	v_fmac_f32_e32 v102, v50, v50
	v_fmac_f32_e32 v103, v52, v52
	s_waitcnt lgkmcnt(0)
	v_add_f32_e32 v81, v81, v83
	ds_bpermute_b32 v83, v90, v81
	v_add_f32_e32 v100, v100, v101
	v_add_f32_e32 v16, v16, v85
	v_add_f32_e32 v101, v102, v103
	v_add_f32_e32 v16, v16, v100
	s_waitcnt lgkmcnt(0)
	v_add_f32_e32 v81, v81, v83
	v_add_f32_e32 v16, v16, v101
	ds_bpermute_b32 v83, v91, v81
	ds_bpermute_b32 v85, v86, v16
	v_lshlrev_b64 v[100:101], 11, v[74:75]
	v_lshl_add_u64 v[100:101], v[78:79], 0, v[100:101]
	s_waitcnt lgkmcnt(1)
	v_add_f32_e32 v81, v81, v83
	s_waitcnt lgkmcnt(0)
	v_add_f32_e32 v16, v16, v85
	v_fmamk_f32 v81, v81, 0x3a800000, v231
	ds_bpermute_b32 v75, v87, v16
	v_mul_f32_e32 v83, 0x4b800000, v81
	v_cmp_gt_f32_e32 vcc, s33, v81
	s_waitcnt lgkmcnt(0)
	v_add_f32_e32 v16, v16, v75
	v_cndmask_b32_e32 v81, v81, v83, vcc
	v_rsq_f32_e32 v81, v81
	ds_bpermute_b32 v75, v88, v16
	v_mul_f32_e32 v83, 0x45800000, v81
	v_cndmask_b32_e32 v81, v81, v83, vcc
	v_mul_f32_e32 v83, v92, v81
	v_mul_f32_e32 v85, v93, v81
	v_mul_f32_e32 v92, v94, v81
	v_mul_f32_e32 v93, v95, v81
	v_mul_f32_e32 v70, v70, v81
	v_mul_f32_e32 v71, v71, v81
	v_mul_f32_e32 v94, v96, v81
	v_mul_f32_e32 v95, v97, v81
	v_mul_f32_e32 v96, v98, v81
	v_mul_f32_e32 v97, v99, v81
	v_mul_f32_e32 v83, v0, v83
	v_mul_f32_e32 v85, v1, v85
	v_mul_f32_e32 v92, v2, v92
	v_mul_f32_e32 v93, v3, v93
	v_mul_f32_e32 v98, v8, v70
	v_mul_f32_e32 v99, v9, v71
	v_cvt_pk_bf16_f32 v70, v83, v85
	v_cvt_pk_bf16_f32 v71, v92, v93
	v_mul_f32_e32 v94, v4, v94
	v_mul_f32_e32 v95, v5, v95
	v_mul_f32_e32 v96, v6, v96
	v_mul_f32_e32 v97, v7, v97
	v_cvt_pk_bf16_f32 v92, v94, v95
	v_cvt_pk_bf16_f32 v93, v96, v97
	global_store_dwordx2 v[100:101], v[70:71], off
	global_store_dwordx2 v[100:101], v[92:93], off offset:512
	v_mul_f32_e32 v70, v73, v81
	v_mul_f32_e32 v72, v72, v81
	v_mul_f32_e32 v70, v11, v70
	s_waitcnt lgkmcnt(0)
	v_add_f32_e32 v16, v16, v75
	v_mul_f32_e32 v102, v10, v72
	v_cvt_pk_bf16_f32 v73, v102, v70
	ds_bpermute_b32 v70, v89, v16
	v_mul_f32_e32 v66, v66, v81
	v_mul_f32_e32 v66, v12, v66
	v_mul_f32_e32 v67, v67, v81
	v_mul_f32_e32 v67, v13, v67
	s_waitcnt lgkmcnt(0)
	v_add_f32_e32 v16, v16, v70
	ds_bpermute_b32 v71, v90, v16
	v_cvt_pk_bf16_f32 v70, v66, v67
	v_mul_f32_e32 v66, v68, v81
	v_mul_f32_e32 v67, v14, v66
	v_mul_f32_e32 v68, v69, v81
	s_waitcnt lgkmcnt(0)
	v_add_f32_e32 v16, v16, v71
	ds_bpermute_b32 v66, v91, v16
	v_cmp_gt_i32_e32 vcc, s47, v84
	v_cvt_pk_bf16_f32 v72, v98, v99
	global_store_dwordx2 v[100:101], v[72:73], off offset:1024
	v_mul_f32_e32 v68, v15, v68
	v_cvt_pk_bf16_f32 v71, v67, v68
	global_store_dwordx2 v[100:101], v[70:71], off offset:1536
	s_and_saveexec_b64 s[12:13], vcc
	s_cbranch_execz .LBB0_1152
	s_waitcnt lgkmcnt(0)
	v_add_f32_e32 v16, v16, v66
	v_fmamk_f32 v16, v16, 0x3a800000, v231
	v_mul_f32_e32 v66, 0x4b800000, v16
	v_cmp_gt_f32_e32 vcc, s33, v16
	v_ashrrev_i32_e32 v85, 31, v84
	s_nop 0
	v_cndmask_b32_e32 v16, v16, v66, vcc
	v_rsq_f32_e32 v16, v16
	v_lshlrev_b64 v[66:67], 11, v[84:85]
	v_lshl_add_u64 v[66:67], v[78:79], 0, v[66:67]
	v_mul_f32_e32 v68, 0x45800000, v16
	v_cndmask_b32_e32 v16, v16, v68, vcc
	v_mul_f32_e32 v62, v62, v16
	v_mul_f32_e32 v63, v63, v16
	v_mul_f32_e32 v58, v58, v16
	v_mul_f32_e32 v59, v59, v16
	v_mul_f32_e32 v54, v54, v16
	v_mul_f32_e32 v55, v55, v16
	v_mul_f32_e32 v50, v50, v16
	v_mul_f32_e32 v51, v51, v16
	v_mul_f32_e32 v62, v0, v62
	v_mul_f32_e32 v63, v1, v63
	v_mul_f32_e32 v58, v4, v58
	v_mul_f32_e32 v59, v5, v59
	v_mul_f32_e32 v54, v8, v54
	v_mul_f32_e32 v55, v9, v55
	v_mul_f32_e32 v50, v12, v50
	v_mul_f32_e32 v51, v13, v51
	v_cvt_pk_bf16_f32 v62, v62, v63
	v_mul_f32_e32 v63, v64, v16
	v_cvt_pk_bf16_f32 v58, v58, v59
	v_mul_f32_e32 v59, v60, v16
	v_cvt_pk_bf16_f32 v54, v54, v55
	v_mul_f32_e32 v55, v56, v16
	v_cvt_pk_bf16_f32 v50, v50, v51
	v_mul_f32_e32 v51, v52, v16
	v_mul_f32_e32 v63, v2, v63
	v_mul_f32_e32 v64, v65, v16
	v_mul_f32_e32 v59, v6, v59
	v_mul_f32_e32 v60, v61, v16
	v_mul_f32_e32 v55, v10, v55
	v_mul_f32_e32 v56, v57, v16
	v_mul_f32_e32 v51, v14, v51
	v_mul_f32_e32 v16, v53, v16
	v_mul_f32_e32 v64, v3, v64
	v_cvt_pk_bf16_f32 v63, v63, v64
	global_store_dwordx2 v[66:67], v[62:63], off
	v_mul_f32_e32 v60, v7, v60
	v_cvt_pk_bf16_f32 v59, v59, v60
	global_store_dwordx2 v[66:67], v[58:59], off offset:512
	v_mul_f32_e32 v56, v11, v56
	v_cvt_pk_bf16_f32 v55, v55, v56
	global_store_dwordx2 v[66:67], v[54:55], off offset:1024
	v_mul_f32_e32 v16, v15, v16
	v_cvt_pk_bf16_f32 v51, v51, v16
	global_store_dwordx2 v[66:67], v[50:51], off offset:1536
